# workgroup index remapped to (rank in XCC)*8 + xcc; in-proj->attention, proj->out, up->down grid barriers made XCC-local (cross-XCC stage skipped) when grid==256
# speedup vs baseline: 1.0120x; 1.0120x over previous
_Z6mk_fwd4Args:
	s_load_dword s33, s[0:1], 0xa0
	s_mov_b64 s[92:93], s[0:1]
	v_and_b32_e32 v1, 0x3ff, v0
	s_add_u32 s8, s92, 0xa0
	s_getreg_b32 s0, hwreg(HW_REG_XCC_ID, 0, 4)
	v_readfirstlane_b32 s74, v1
	s_addc_u32 s9, s93, 0
	s_and_b32 s75, s0, 15
	v_cmp_eq_u32_e32 vcc, 0, v1
	s_and_saveexec_b64 s[0:1], vcc
	s_cbranch_execz .LBB0_3
	s_add_i32 s3, 0, 0x20100
	v_mov_b32_e32 v2, 0
	v_mov_b32_e32 v3, s3
	s_add_i32 s3, 0, 0x20104
	s_mov_b64 s[4:5], exec
	ds_write_b32 v3, v2
	v_mov_b32_e32 v3, s3
	ds_write_b32 v3, v2
	v_mbcnt_lo_u32_b32 v2, s4, 0
	v_mbcnt_hi_u32_b32 v2, s5, v2
	v_cmp_eq_u32_e32 vcc, 0, v2
	s_and_b64 s[6:7], exec, vcc
	s_mov_b64 exec, s[6:7]
	s_cbranch_execz .LBB0_3
	s_load_dwordx2 s[6:7], s[92:93], 0x78
	s_lshl_b32 s3, s75, 8
	v_mov_b32_e32 v2, 0xf0000
	s_waitcnt lgkmcnt(0)
	s_add_u32 s6, s6, s3
	s_addc_u32 s7, s7, 0
	s_bcnt1_i32_b64 s3, s[4:5]
	v_mov_b32_e32 v3, s3
	global_atomic_add v3, v2, v3, s[6:7] offset:1024 sc0
	s_waitcnt vmcnt(0)
	v_lshlrev_b32_e32 v3, 3, v3
	v_or_b32_e32 v3, s75, v3
	v_mov_b32_e32 v2, 0x20108
	ds_write_b32 v2, v3
.LBB0_3:
	s_or_b64 exec, exec, s[0:1]
	s_waitcnt lgkmcnt(0)
	s_barrier
	s_cmp_eq_u32 s33, 0x100
	s_cbranch_scc0 .Lno_remap
	v_mov_b32_e32 v2, 0x20108
	ds_read_b32 v2, v2
	s_waitcnt lgkmcnt(0)
	v_readfirstlane_b32 s2, v2
	s_nop 3
.Lno_remap:
	s_load_dwordx2 s[0:1], s[8:9], 0x4
	s_load_dwordx2 s[76:77], s[92:93], 0x78
	s_waitcnt lgkmcnt(0)
	s_lshl_b32 s36, s33, 3
	s_lshr_b32 s91, s74, 6
	s_lshl_b32 s3, s2, 3
	s_mov_b32 s4, s36
	v_writelane_b32 v252, s76, 0
	s_add_i32 s90, s91, s3
	s_cmpk_gt_i32 s90, 0x4ff
	v_writelane_b32 v252, s77, 1
	v_writelane_b32 v252, s4, 2
	v_and_b32_e32 v2, 63, v1
	s_nop 0
	v_writelane_b32 v252, s5, 3
	s_cbranch_scc1 .LBB0_9
	s_load_dwordx4 s[4:7], s[92:93], 0x10
	s_add_u32 s10, s76, 0x200000
	s_addc_u32 s11, s77, 0
	v_mov_b32_e32 v5, 0
	s_movk_i32 s21, 0x5000
	s_waitcnt lgkmcnt(0)
	s_cmp_lg_u64 s[4:5], 0
	s_cselect_b64 s[12:13], -1, 0
	s_lshl_b32 s3, s90, 6
	s_lshl_b32 s20, s36, 6
	v_lshlrev_b32_e32 v4, 2, v2
	s_mov_b32 s22, 0xa000
	s_mov_b32 s23, 0xf000
	s_mov_b32 s24, 0x14000
	s_mov_b32 s25, 0x19000
	s_mov_b32 s26, 0x1e000
	s_mov_b32 s27, 0x23000
	s_mov_b32 s28, 0x28000
	s_mov_b32 s29, 0x2d000
	s_mov_b32 s30, 0x32000
	s_mov_b32 s31, 0x37000
	s_mov_b32 s34, 0x3c000
	s_mov_b32 s35, 0x41000
	s_mov_b32 s36, 0x46000
	s_mov_b32 s37, 0x4b000
	s_mov_b32 s38, 0x50000
	s_mov_b32 s39, 0x55000
	s_mov_b32 s40, 0x5a000
	s_mov_b32 s41, 0x5f000
	s_mov_b32 s42, 0x64000
	s_mov_b32 s43, 0x69000
	s_mov_b32 s44, 0x6e000
	s_mov_b32 s45, 0x73000
	s_mov_b32 s46, 0x78000
	s_mov_b32 s47, 0x7d000
	s_mov_b32 s48, 0x82000
	s_mov_b32 s49, 0x87000
	s_mov_b32 s50, 0x8c000
	s_mov_b32 s51, 0x91000
	s_mov_b32 s52, 0x96000
	s_mov_b32 s53, 0x9b000
	s_mov_b32 s54, 0xa0000
	s_mov_b32 s55, 0xa5000
	s_mov_b32 s56, 0xaa000
	s_mov_b32 s57, 0xaf000
	s_mov_b32 s59, 0xb4000
	s_mov_b32 s60, 0xb9000
	s_mov_b32 s61, 0xbe000
	s_mov_b32 s62, 0xc3000
	s_mov_b32 s63, 0xc8000
	s_mov_b32 s64, 0xcd000
	s_mov_b32 s65, 0xd2000
	s_mov_b32 s66, 0xd7000
	s_mov_b32 s67, 0xdc000
	s_mov_b32 s68, 0xe1000
	s_mov_b32 s69, 0xe6000
	s_mov_b32 s70, 0xeb000
	s_mov_b32 s71, 0xf0000
	s_mov_b32 s72, 0xf5000
	s_mov_b32 s73, 0xfa000
	s_mov_b32 s76, 0xff000
	s_mov_b32 s77, 0x104000
	s_mov_b32 s78, 0x109000
	s_mov_b32 s79, 0x10e000
	s_mov_b32 s80, 0x113000
	s_mov_b32 s81, 0x118000
	s_mov_b32 s82, 0x11d000
	s_mov_b32 s83, 0x122000
	s_mov_b32 s84, 0x127000
	s_mov_b32 s85, 0x12c000
	s_mov_b32 s86, s90
	s_branch .LBB0_6

.LBB0_342:
	s_andn2_saveexec_b64 s[0:1], s[0:1]
	s_cbranch_execz .LBB0_362
	s_mov_b64 s[0:1], exec
	buffer_wbl2 sc1
	s_waitcnt lgkmcnt(0)
	s_waitcnt vmcnt(0)
	s_cmp_eq_u32 s33, 0x100
	s_cbranch_scc1 .LBB0_359
	v_mbcnt_lo_u32_b32 v1, s0, 0
	v_mbcnt_hi_u32_b32 v1, s1, v1
	v_cmp_eq_u32_e32 vcc, 0, v1
	s_and_saveexec_b64 s[6:7], vcc
	s_cbranch_execz .LBB0_345
	s_bcnt1_i32_b64 s0, s[0:1]
	v_mov_b32_e32 v2, s0
	v_readlane_b32 s0, v253, 15
	v_readlane_b32 s1, v253, 16
	s_nop 4
	global_atomic_add v2, v177, v2, s[0:1] sc0
